# EpiInproj epilogue rewritten: one uniform branch, straight-line cvt + 16-byte stores with 32-bit offsets
# speedup vs baseline: 1.0085x; 1.0026x over previous
; __device__ __forceinline__ unsigned cvt_pk_bf16(float lo, float hi) { unsigned r; asm("v_cvt_pk_bf16_f32 %0, %1, %2" : "=v"(r) : "v"(lo), "v"(hi)); return r; }
;     __device__ __forceinline__ void operator()(const Acc& acc, const Unit& u, int wr, int wc, int fr, int fq) const {
;         const int row0 = u.pm * 256 + wr * 64 + fr;
; #pragma unroll
;         for (int ai = 0; ai < 2; ++ai)
; #pragma unroll
;             for (int m = 0; m < 4; ++m) { const int row = row0 + ai * 128 + m * 16;
; #pragma unroll
;                 for (int bj = 0; bj < 2; ++bj) { const f32x4 a = acc[ai][bj][m][0], b = acc[ai][bj][m][1];
;                     u32x4 w; w.x = cvt_pk_bf16(a[0], a[1]); w.y = cvt_pk_bf16(a[2], a[3]); w.z = cvt_pk_bf16(b[0], b[1]); w.w = cvt_pk_bf16(b[2], b[3]);
;                     if (u.pn < 3) { const int col = u.pn * 256 + bj * 128 + wc * 32 + 8 * fq; *(u32x4*)(QKV + (size_t)row * QKVW + col) = w; }
;                     else { const int g = (u.pn - 3) * 16 + bj * 8 + wc * 2 + (fq >> 1); *(u32x4*)(A2 + ((size_t)g * A2ROWS + (row >> 5)) * A2K + (row & 31) * 16 + 8 * (fq & 1)) = w; } } }
;     }
.LBB0_489:
	s_lshl_b32 s13, s6, 8
	s_add_i32 s13, s13, s50
	v_cvt_pk_bf16_f32 v124, v124, v125
	v_cvt_pk_bf16_f32 v125, v126, v127
	v_cvt_pk_bf16_f32 v126, v120, v121
	v_cvt_pk_bf16_f32 v127, v122, v123
	v_cvt_pk_bf16_f32 v116, v116, v117
	v_cvt_pk_bf16_f32 v117, v118, v119
	v_cvt_pk_bf16_f32 v118, v112, v113
	v_cvt_pk_bf16_f32 v119, v114, v115
	v_cvt_pk_bf16_f32 v108, v108, v109
	v_cvt_pk_bf16_f32 v109, v110, v111
	v_cvt_pk_bf16_f32 v110, v104, v105
	v_cvt_pk_bf16_f32 v111, v106, v107
	v_cvt_pk_bf16_f32 v100, v100, v101
	v_cvt_pk_bf16_f32 v101, v102, v103
	v_cvt_pk_bf16_f32 v102, v96, v97
	v_cvt_pk_bf16_f32 v103, v98, v99
	v_cvt_pk_bf16_f32 v92, v92, v93
	v_cvt_pk_bf16_f32 v93, v94, v95
	v_cvt_pk_bf16_f32 v94, v88, v89
	v_cvt_pk_bf16_f32 v95, v90, v91
	v_cvt_pk_bf16_f32 v84, v84, v85
	v_cvt_pk_bf16_f32 v85, v86, v87
	v_cvt_pk_bf16_f32 v86, v80, v81
	v_cvt_pk_bf16_f32 v87, v82, v83
	v_cvt_pk_bf16_f32 v76, v76, v77
	v_cvt_pk_bf16_f32 v77, v78, v79
	v_cvt_pk_bf16_f32 v78, v72, v73
	v_cvt_pk_bf16_f32 v79, v74, v75
	v_cvt_pk_bf16_f32 v68, v68, v69
	v_cvt_pk_bf16_f32 v69, v70, v71
	v_cvt_pk_bf16_f32 v70, v64, v65
	v_cvt_pk_bf16_f32 v71, v66, v67
	v_cvt_pk_bf16_f32 v60, v60, v61
	v_cvt_pk_bf16_f32 v61, v62, v63
	v_cvt_pk_bf16_f32 v62, v56, v57
	v_cvt_pk_bf16_f32 v63, v58, v59
	v_cvt_pk_bf16_f32 v52, v52, v53
	v_cvt_pk_bf16_f32 v53, v54, v55
	v_cvt_pk_bf16_f32 v54, v48, v49
	v_cvt_pk_bf16_f32 v55, v50, v51
	v_cvt_pk_bf16_f32 v44, v44, v45
	v_cvt_pk_bf16_f32 v45, v46, v47
	v_cvt_pk_bf16_f32 v46, v40, v41
	v_cvt_pk_bf16_f32 v47, v42, v43
	v_cvt_pk_bf16_f32 v36, v36, v37
	v_cvt_pk_bf16_f32 v37, v38, v39
	v_cvt_pk_bf16_f32 v38, v32, v33
	v_cvt_pk_bf16_f32 v39, v34, v35
	v_cvt_pk_bf16_f32 v28, v28, v29
	v_cvt_pk_bf16_f32 v29, v30, v31
	v_cvt_pk_bf16_f32 v30, v24, v25
	v_cvt_pk_bf16_f32 v31, v26, v27
	v_cvt_pk_bf16_f32 v20, v20, v21
	v_cvt_pk_bf16_f32 v21, v22, v23
	v_cvt_pk_bf16_f32 v22, v16, v17
	v_cvt_pk_bf16_f32 v23, v18, v19
	v_cvt_pk_bf16_f32 v12, v12, v13
	v_cvt_pk_bf16_f32 v13, v14, v15
	v_cvt_pk_bf16_f32 v14, v8, v9
	v_cvt_pk_bf16_f32 v15, v10, v11
	v_cvt_pk_bf16_f32 v4, v4, v5
	v_cvt_pk_bf16_f32 v5, v6, v7
	v_cvt_pk_bf16_f32 v6, v0, v1
	v_cvt_pk_bf16_f32 v7, v2, v3
	s_cmp_gt_i32 s56, 2
	s_cbranch_scc1 .Lepi_in_u
	v_or_b32_e32 v152, s13, v135
	v_mul_u32_u24_e32 v152, 0x600, v152
	v_lshl_or_b32 v153, s56, 8, v148
	v_lshl_add_u32 v152, v153, 1, v152
	global_store_dwordx4 v152, v[124:127], s[14:15]
	global_store_dwordx4 v152, v[116:119], s[14:15] offset:256
	v_add_u32_e32 v153, 0x6000, v152
	global_store_dwordx4 v153, v[108:111], s[14:15]
	global_store_dwordx4 v153, v[100:103], s[14:15] offset:256
	v_add_u32_e32 v154, 0xc000, v152
	global_store_dwordx4 v154, v[92:95], s[14:15]
	global_store_dwordx4 v154, v[84:87], s[14:15] offset:256
	v_add_u32_e32 v153, 0x12000, v152
	global_store_dwordx4 v153, v[76:79], s[14:15]
	global_store_dwordx4 v153, v[68:71], s[14:15] offset:256
	v_add_u32_e32 v154, 0x30000, v152
	global_store_dwordx4 v154, v[60:63], s[14:15]
	global_store_dwordx4 v154, v[52:55], s[14:15] offset:256
	v_add_u32_e32 v153, 0x36000, v152
	global_store_dwordx4 v153, v[44:47], s[14:15]
	global_store_dwordx4 v153, v[36:39], s[14:15] offset:256
	v_add_u32_e32 v154, 0x3c000, v152
	global_store_dwordx4 v154, v[28:31], s[14:15]
	global_store_dwordx4 v154, v[20:23], s[14:15] offset:256
	v_add_u32_e32 v153, 0x42000, v152
	global_store_dwordx4 v153, v[12:15], s[14:15]
	global_store_dwordx4 v153, v[4:7], s[14:15] offset:256
	s_branch .Lepi_in_done
.Lepi_in_u:
	s_ashr_i32 s40, s13, 5
	v_lshl_add_u32 v152, s56, 4, v147
	v_mul_u32_u24_e32 v152, 0x500, v152
	v_add_u32_e32 v152, s40, v152
	v_mul_u32_u24_e32 v152, 0x600, v152
	v_lshlrev_b32_e32 v153, 5, v135
	v_lshl_add_u32 v153, v134, 1, v153
	v_add_u32_e32 v152, v152, v153
	v_add_u32_e32 v155, 0xf00000, v152
	global_store_dwordx4 v152, v[124:127], s[22:23]
	global_store_dwordx4 v155, v[116:119], s[22:23]
	v_add_u32_e32 v153, 0x200, v152
	global_store_dwordx4 v153, v[108:111], s[22:23]
	v_add_u32_e32 v154, 0x200, v155
	global_store_dwordx4 v154, v[100:103], s[22:23]
	v_add_u32_e32 v153, 0x600, v152
	global_store_dwordx4 v153, v[92:95], s[22:23]
	v_add_u32_e32 v154, 0x600, v155
	global_store_dwordx4 v154, v[84:87], s[22:23]
	v_add_u32_e32 v153, 0x800, v152
	global_store_dwordx4 v153, v[76:79], s[22:23]
	v_add_u32_e32 v154, 0x800, v155
	global_store_dwordx4 v154, v[68:71], s[22:23]
	v_add_u32_e32 v153, 0x1800, v152
	global_store_dwordx4 v153, v[60:63], s[22:23]
	v_add_u32_e32 v154, 0x1800, v155
	global_store_dwordx4 v154, v[52:55], s[22:23]
	v_add_u32_e32 v153, 0x1a00, v152
	global_store_dwordx4 v153, v[44:47], s[22:23]
	v_add_u32_e32 v154, 0x1a00, v155
	global_store_dwordx4 v154, v[36:39], s[22:23]
	v_add_u32_e32 v153, 0x1e00, v152
	global_store_dwordx4 v153, v[28:31], s[22:23]
	v_add_u32_e32 v154, 0x1e00, v155
	global_store_dwordx4 v154, v[20:23], s[22:23]
	v_add_u32_e32 v153, 0x2000, v152
	global_store_dwordx4 v153, v[12:15], s[22:23]
	v_add_u32_e32 v154, 0x2000, v155
	global_store_dwordx4 v154, v[4:7], s[22:23]
.Lepi_in_done:
	s_andn2_b64 vcc, exec, s[4:5]
	s_mov_b64 s[4:5], -1
	s_cbranch_vccnz .LBB0_482
.LBB0_554:
	s_andn2_b64 vcc, exec, s[0:1]
	s_cbranch_vccnz .LBB0_481
	s_barrier
	s_branch .LBB0_481
